# S5: per-wave LDS images re-laid (HS of all waves below 64 KiB) so the scan's h writes use ds_write_addtid_b32 (M0 base, no address VGPR) (v60 + addtid)
# baseline (speedup 1.0000x reference)
.LBB0_769:
	s_or_b64 exec, exec, s[14:15]
	v_mov_b32_e32 v1, s35
	s_waitcnt lgkmcnt(0)
	s_barrier
	ds_read_b32 v1, v1
	s_waitcnt lgkmcnt(0)
	v_readfirstlane_b32 s37, v1
	s_cmpk_gt_i32 s37, 0xbf
	s_cbranch_scc1 .LBB0_923
	v_writelane_b32 v255, s16, 22
	s_mul_i32 s2, s6, 0x3200
	s_add_i32 s2, s2, 0
	v_writelane_b32 v255, s17, 23
	s_lshl_b32 s16, s6, 2
	s_addk_i32 s16, 0xf800
	s_add_u32 s20, s12, 0x42e00000
	s_addc_u32 s21, s13, 0
	v_ashrrev_i32_e32 v2, 4, v0
	s_add_u32 s22, s0, 0x6000000
	v_cmp_gt_i32_e64 s[40:41], 2, v2
	v_cmp_lt_i32_e64 s[42:43], 1, v2
	v_lshlrev_b32_e32 v4, 3, v2
	v_lshlrev_b32_e32 v86, 2, v2
	s_mul_i32 s2, s6, 0x2100
	s_add_i32 s2, s2, 0x8800
	v_mov_b32_e32 v2, s2
	v_lshl_add_u32 v95, v0, 3, s2
	s_addc_u32 s23, s1, 0
	s_and_b32 s2, s6, 1
	s_lshl_b32 s0, s2, 7
	v_writelane_b32 v255, s18, 24
	s_or_b32 s24, s0, s8
	v_readlane_b32 s0, v254, 59
	v_writelane_b32 v255, s19, 25
	s_or_b32 s0, s2, s0
	v_writelane_b32 v255, s0, 26
	s_mul_i32 s0, s2, 0x1800000
	s_add_u32 s0, s20, s0
	v_ashrrev_i32_e32 v5, 31, v4
	v_and_b32_e32 v6, 1, v0
	v_ashrrev_i32_e32 v87, 31, v86
	s_addc_u32 s1, s21, 0
	v_bfe_u32 v84, v0, 1, 3
	v_cmp_eq_u32_e64 s[44:45], 0, v6
	v_lshl_add_u64 v[6:7], v[4:5], 1, s[12:13]
	s_mov_b64 s[12:13], 0x2c600000
	s_cmp_eq_u32 s2, 0
	v_lshl_add_u64 v[110:111], v[86:87], 1, s[0:1]
	v_readlane_b32 s0, v254, 55
	v_lshlrev_b64 v[4:5], 2, v[4:5]
	v_and_b32_e32 v85, 15, v0
	v_lshl_add_u64 v[90:91], v[6:7], 0, s[12:13]
	s_movk_i32 s3, 0x210
	v_lshlrev_b32_e32 v6, 2, v0
	v_lshlrev_b32_e32 v92, 4, v84
	v_lshlrev_b32_e32 v108, 1, v0
	s_cselect_b64 s[54:55], -1, 0
	s_or_b32 s0, s2, s0
	v_lshl_add_u64 v[112:113], s[72:73], 0, v[4:5]
	v_lshl_add_u64 v[114:115], s[74:75], 0, v[4:5]
	v_lshlrev_b64 v[4:5], 2, v[86:87]
	v_ashrrev_i32_e32 v1, 31, v0
	v_lshlrev_b32_e32 v88, 6, v85
	v_mad_u32_u24 v89, v85, s3, v2
	v_and_b32_e32 v93, -16, v0
	s_mul_i32 s3, s6, 0x1100
	v_add_u32_e32 v97, s3, v6
	v_mul_u32_u24_e32 v99, s30, v85
	v_add_u32_e32 v99, s3, v99
	v_or_b32_e32 v94, 0x80, v92
	v_or_b32_e32 v96, 0x100, v92
	v_or_b32_e32 v98, 0x180, v92
	v_or_b32_e32 v100, 0x200, v92
	v_or_b32_e32 v102, 0x280, v92
	v_or_b32_e32 v104, 0x300, v92
	v_or_b32_e32 v106, 0x380, v92
	v_ashrrev_i32_e32 v109, 31, v108
	v_writelane_b32 v255, s0, 28
	v_lshl_add_u64 v[116:117], s[76:77], 0, v[4:5]
	v_lshl_add_u64 v[118:119], s[78:79], 0, v[4:5]
	s_branch .LBB0_774

.LBB0_844:
	s_or_b64 exec, exec, s[12:13]
	v_readfirstlane_b32 s14, v97
	s_mov_b32 m0, s14
	v_mfma_f32_16x16x32_bf16 v[132:135], v[4:7], v[68:71], 0
	v_mfma_f32_16x16x32_bf16 v[136:139], v[8:11], v[68:71], 0
	v_mfma_f32_16x16x32_bf16 v[140:143], v[12:15], v[68:71], 0
	v_mfma_f32_16x16x32_bf16 v[144:147], v[16:19], v[68:71], 0
	v_mfma_f32_16x16x32_bf16 v[148:151], v[20:23], v[68:71], 0
	v_mfma_f32_16x16x32_bf16 v[152:155], v[24:27], v[68:71], 0
	v_mfma_f32_16x16x32_bf16 v[156:159], v[28:31], v[68:71], 0
	v_mfma_f32_16x16x32_bf16 v[160:163], v[32:35], v[68:71], 0
	v_add_u32_e32 v196, v89, v93
	ds_write_b128 v196, v[132:135]
	ds_write_b128 v196, v[136:139] offset:64
	ds_write_b128 v196, v[140:143] offset:128
	ds_write_b128 v196, v[144:147] offset:192
	ds_write_b128 v196, v[148:151] offset:256
	ds_write_b128 v196, v[152:155] offset:320
	ds_write_b128 v196, v[156:159] offset:384
	ds_write_b128 v196, v[160:163] offset:448
	s_waitcnt lgkmcnt(0)
	s_and_b64 s[14:15], s[0:1], exec
	s_cbranch_scc0 .Ls5c_bwd
	ds_read_b64 v[164:165], v95
	ds_read_b64 v[166:167], v95 offset:528
	ds_read_b64 v[168:169], v95 offset:1056
	ds_read_b64 v[170:171], v95 offset:1584
	ds_read_b64 v[172:173], v95 offset:2112
	ds_read_b64 v[174:175], v95 offset:2640
	ds_read_b64 v[176:177], v95 offset:3168
	ds_read_b64 v[178:179], v95 offset:3696
	s_waitcnt lgkmcnt(7)
	v_fma_f32 v164, -v72, v121, v164
	v_fma_f32 v165, v72, v120, v165
	v_fma_f32 v164, v74, v120, v164
	v_fma_f32 v165, v74, v121, v165
	v_cvt_pk_bf16_f32 v197, v164, v165
	ds_write_addtid_b32 v197
	ds_read_b64 v[180:181], v95 offset:4224
	s_waitcnt lgkmcnt(8)
	v_fma_f32 v166, -v72, v165, v166
	v_fma_f32 v167, v72, v164, v167
	v_fma_f32 v166, v74, v164, v166
	v_fma_f32 v167, v74, v165, v167
	v_cvt_pk_bf16_f32 v198, v166, v167
	ds_write_addtid_b32 v198 offset:272
	ds_read_b64 v[182:183], v95 offset:4752
	s_waitcnt lgkmcnt(9)
	v_fma_f32 v168, -v72, v167, v168
	v_fma_f32 v169, v72, v166, v169
	v_fma_f32 v168, v74, v166, v168
	v_fma_f32 v169, v74, v167, v169
	v_cvt_pk_bf16_f32 v197, v168, v169
	ds_write_addtid_b32 v197 offset:544
	ds_read_b64 v[184:185], v95 offset:5280
	s_waitcnt lgkmcnt(10)
	v_fma_f32 v170, -v72, v169, v170
	v_fma_f32 v171, v72, v168, v171
	v_fma_f32 v170, v74, v168, v170
	v_fma_f32 v171, v74, v169, v171
	v_cvt_pk_bf16_f32 v198, v170, v171
	ds_write_addtid_b32 v198 offset:816
	ds_read_b64 v[186:187], v95 offset:5808
	s_waitcnt lgkmcnt(11)
	v_fma_f32 v172, -v72, v171, v172
	v_fma_f32 v173, v72, v170, v173
	v_fma_f32 v172, v74, v170, v172
	v_fma_f32 v173, v74, v171, v173
	v_cvt_pk_bf16_f32 v197, v172, v173
	ds_write_addtid_b32 v197 offset:1088
	ds_read_b64 v[188:189], v95 offset:6336
	s_waitcnt lgkmcnt(12)
	v_fma_f32 v174, -v72, v173, v174
	v_fma_f32 v175, v72, v172, v175
	v_fma_f32 v174, v74, v172, v174
	v_fma_f32 v175, v74, v173, v175
	v_cvt_pk_bf16_f32 v198, v174, v175
	ds_write_addtid_b32 v198 offset:1360
	ds_read_b64 v[190:191], v95 offset:6864
	s_waitcnt lgkmcnt(13)
	v_fma_f32 v176, -v72, v175, v176
	v_fma_f32 v177, v72, v174, v177
	v_fma_f32 v176, v74, v174, v176
	v_fma_f32 v177, v74, v175, v177
	v_cvt_pk_bf16_f32 v197, v176, v177
	ds_write_addtid_b32 v197 offset:1632
	ds_read_b64 v[192:193], v95 offset:7392
	s_waitcnt lgkmcnt(14)
	v_fma_f32 v178, -v72, v177, v178
	v_fma_f32 v179, v72, v176, v179
	v_fma_f32 v178, v74, v176, v178
	v_fma_f32 v179, v74, v177, v179
	v_cvt_pk_bf16_f32 v198, v178, v179
	ds_write_addtid_b32 v198 offset:1904
	ds_read_b64 v[194:195], v95 offset:7920
	s_waitcnt lgkmcnt(14)
	v_fma_f32 v180, -v72, v179, v180
	v_fma_f32 v181, v72, v178, v181
	v_fma_f32 v180, v74, v178, v180
	v_fma_f32 v181, v74, v179, v181
	v_cvt_pk_bf16_f32 v197, v180, v181
	ds_write_addtid_b32 v197 offset:2176
	s_waitcnt lgkmcnt(13)
	v_fma_f32 v182, -v72, v181, v182
	v_fma_f32 v183, v72, v180, v183
	v_fma_f32 v182, v74, v180, v182
	v_fma_f32 v183, v74, v181, v183
	v_cvt_pk_bf16_f32 v198, v182, v183
	ds_write_addtid_b32 v198 offset:2448
	s_waitcnt lgkmcnt(12)
	v_fma_f32 v184, -v72, v183, v184
	v_fma_f32 v185, v72, v182, v185
	v_fma_f32 v184, v74, v182, v184
	v_fma_f32 v185, v74, v183, v185
	v_cvt_pk_bf16_f32 v197, v184, v185
	ds_write_addtid_b32 v197 offset:2720
	s_waitcnt lgkmcnt(11)
	v_fma_f32 v186, -v72, v185, v186
	v_fma_f32 v187, v72, v184, v187
	v_fma_f32 v186, v74, v184, v186
	v_fma_f32 v187, v74, v185, v187
	v_cvt_pk_bf16_f32 v198, v186, v187
	ds_write_addtid_b32 v198 offset:2992
	s_waitcnt lgkmcnt(10)
	v_fma_f32 v188, -v72, v187, v188
	v_fma_f32 v189, v72, v186, v189
	v_fma_f32 v188, v74, v186, v188
	v_fma_f32 v189, v74, v187, v189
	v_cvt_pk_bf16_f32 v197, v188, v189
	ds_write_addtid_b32 v197 offset:3264
	s_waitcnt lgkmcnt(9)
	v_fma_f32 v190, -v72, v189, v190
	v_fma_f32 v191, v72, v188, v191
	v_fma_f32 v190, v74, v188, v190
	v_fma_f32 v191, v74, v189, v191
	v_cvt_pk_bf16_f32 v198, v190, v191
	ds_write_addtid_b32 v198 offset:3536
	s_waitcnt lgkmcnt(8)
	v_fma_f32 v192, -v72, v191, v192
	v_fma_f32 v193, v72, v190, v193
	v_fma_f32 v192, v74, v190, v192
	v_fma_f32 v193, v74, v191, v193
	v_cvt_pk_bf16_f32 v197, v192, v193
	ds_write_addtid_b32 v197 offset:3808
	s_waitcnt lgkmcnt(7)
	v_fma_f32 v194, -v72, v193, v194
	v_fma_f32 v195, v72, v192, v195
	v_fma_f32 v194, v74, v192, v194
	v_fma_f32 v195, v74, v193, v195
	v_cvt_pk_bf16_f32 v198, v194, v195
	ds_write_addtid_b32 v198 offset:4080
	s_branch .Ls5c_join
.Ls5c_bwd:
	ds_read_b64 v[164:165], v95 offset:7920
	ds_read_b64 v[166:167], v95 offset:7392
	ds_read_b64 v[168:169], v95 offset:6864
	ds_read_b64 v[170:171], v95 offset:6336
	ds_read_b64 v[172:173], v95 offset:5808
	ds_read_b64 v[174:175], v95 offset:5280
	ds_read_b64 v[176:177], v95 offset:4752
	ds_read_b64 v[178:179], v95 offset:4224
	s_waitcnt lgkmcnt(7)
	v_fma_f32 v164, -v72, v121, v164
	v_fma_f32 v165, v72, v120, v165
	v_fma_f32 v164, v74, v120, v164
	v_fma_f32 v165, v74, v121, v165
	v_cvt_pk_bf16_f32 v197, v164, v165
	ds_write_addtid_b32 v197 offset:4080
	ds_read_b64 v[180:181], v95 offset:3696
	s_waitcnt lgkmcnt(8)
	v_fma_f32 v166, -v72, v165, v166
	v_fma_f32 v167, v72, v164, v167
	v_fma_f32 v166, v74, v164, v166
	v_fma_f32 v167, v74, v165, v167
	v_cvt_pk_bf16_f32 v198, v166, v167
	ds_write_addtid_b32 v198 offset:3808
	ds_read_b64 v[182:183], v95 offset:3168
	s_waitcnt lgkmcnt(9)
	v_fma_f32 v168, -v72, v167, v168
	v_fma_f32 v169, v72, v166, v169
	v_fma_f32 v168, v74, v166, v168
	v_fma_f32 v169, v74, v167, v169
	v_cvt_pk_bf16_f32 v197, v168, v169
	ds_write_addtid_b32 v197 offset:3536
	ds_read_b64 v[184:185], v95 offset:2640
	s_waitcnt lgkmcnt(10)
	v_fma_f32 v170, -v72, v169, v170
	v_fma_f32 v171, v72, v168, v171
	v_fma_f32 v170, v74, v168, v170
	v_fma_f32 v171, v74, v169, v171
	v_cvt_pk_bf16_f32 v198, v170, v171
	ds_write_addtid_b32 v198 offset:3264
	ds_read_b64 v[186:187], v95 offset:2112
	s_waitcnt lgkmcnt(11)
	v_fma_f32 v172, -v72, v171, v172
	v_fma_f32 v173, v72, v170, v173
	v_fma_f32 v172, v74, v170, v172
	v_fma_f32 v173, v74, v171, v173
	v_cvt_pk_bf16_f32 v197, v172, v173
	ds_write_addtid_b32 v197 offset:2992
	ds_read_b64 v[188:189], v95 offset:1584
	s_waitcnt lgkmcnt(12)
	v_fma_f32 v174, -v72, v173, v174
	v_fma_f32 v175, v72, v172, v175
	v_fma_f32 v174, v74, v172, v174
	v_fma_f32 v175, v74, v173, v175
	v_cvt_pk_bf16_f32 v198, v174, v175
	ds_write_addtid_b32 v198 offset:2720
	ds_read_b64 v[190:191], v95 offset:1056
	s_waitcnt lgkmcnt(13)
	v_fma_f32 v176, -v72, v175, v176
	v_fma_f32 v177, v72, v174, v177
	v_fma_f32 v176, v74, v174, v176
	v_fma_f32 v177, v74, v175, v177
	v_cvt_pk_bf16_f32 v197, v176, v177
	ds_write_addtid_b32 v197 offset:2448
	ds_read_b64 v[192:193], v95 offset:528
	s_waitcnt lgkmcnt(14)
	v_fma_f32 v178, -v72, v177, v178
	v_fma_f32 v179, v72, v176, v179
	v_fma_f32 v178, v74, v176, v178
	v_fma_f32 v179, v74, v177, v179
	v_cvt_pk_bf16_f32 v198, v178, v179
	ds_write_addtid_b32 v198 offset:2176
	ds_read_b64 v[194:195], v95
	s_waitcnt lgkmcnt(14)
	v_fma_f32 v180, -v72, v179, v180
	v_fma_f32 v181, v72, v178, v181
	v_fma_f32 v180, v74, v178, v180
	v_fma_f32 v181, v74, v179, v181
	v_cvt_pk_bf16_f32 v197, v180, v181
	ds_write_addtid_b32 v197 offset:1904
	s_waitcnt lgkmcnt(13)
	v_fma_f32 v182, -v72, v181, v182
	v_fma_f32 v183, v72, v180, v183
	v_fma_f32 v182, v74, v180, v182
	v_fma_f32 v183, v74, v181, v183
	v_cvt_pk_bf16_f32 v198, v182, v183
	ds_write_addtid_b32 v198 offset:1632
	s_waitcnt lgkmcnt(12)
	v_fma_f32 v184, -v72, v183, v184
	v_fma_f32 v185, v72, v182, v185
	v_fma_f32 v184, v74, v182, v184
	v_fma_f32 v185, v74, v183, v185
	v_cvt_pk_bf16_f32 v197, v184, v185
	ds_write_addtid_b32 v197 offset:1360
	s_waitcnt lgkmcnt(11)
	v_fma_f32 v186, -v72, v185, v186
	v_fma_f32 v187, v72, v184, v187
	v_fma_f32 v186, v74, v184, v186
	v_fma_f32 v187, v74, v185, v187
	v_cvt_pk_bf16_f32 v198, v186, v187
	ds_write_addtid_b32 v198 offset:1088
	s_waitcnt lgkmcnt(10)
	v_fma_f32 v188, -v72, v187, v188
	v_fma_f32 v189, v72, v186, v189
	v_fma_f32 v188, v74, v186, v188
	v_fma_f32 v189, v74, v187, v189
	v_cvt_pk_bf16_f32 v197, v188, v189
	ds_write_addtid_b32 v197 offset:816
	s_waitcnt lgkmcnt(9)
	v_fma_f32 v190, -v72, v189, v190
	v_fma_f32 v191, v72, v188, v191
	v_fma_f32 v190, v74, v188, v190
	v_fma_f32 v191, v74, v189, v191
	v_cvt_pk_bf16_f32 v198, v190, v191
	ds_write_addtid_b32 v198 offset:544
	s_waitcnt lgkmcnt(8)
	v_fma_f32 v192, -v72, v191, v192
	v_fma_f32 v193, v72, v190, v193
	v_fma_f32 v192, v74, v190, v192
	v_fma_f32 v193, v74, v191, v193
	v_cvt_pk_bf16_f32 v197, v192, v193
	ds_write_addtid_b32 v197 offset:272
	s_waitcnt lgkmcnt(7)
	v_fma_f32 v194, -v72, v193, v194
	v_fma_f32 v195, v72, v192, v195
	v_fma_f32 v194, v74, v192, v194
	v_fma_f32 v195, v74, v193, v195
	v_cvt_pk_bf16_f32 v198, v194, v195
	ds_write_addtid_b32 v198
.Ls5c_join:
	v_mov_b32_e32 v120, v194
	v_mov_b32_e32 v121, v195
	s_waitcnt lgkmcnt(0)
	v_add_u32_e32 v196, v99, v93
	ds_read_b128 v[132:135], v196
	ds_read_b128 v[136:139], v196 offset:64
	ds_read_b128 v[140:143], v196 offset:128
	ds_read_b128 v[144:147], v196 offset:192
	s_not_b32 s14, s3
	s_add_i32 s18, s2, s14
	s_and_b64 s[14:15], s[0:1], exec
	s_cselect_b32 s14, s3, s18
	s_add_i32 s3, s3, 1
	s_waitcnt lgkmcnt(3)
	v_mfma_f32_16x16x32_bf16 v[68:71], v[48:51], v[132:135], 0
	s_waitcnt lgkmcnt(2)
	v_mfma_f32_16x16x32_bf16 v[68:71], v[52:55], v[136:139], v[68:71]
	s_waitcnt lgkmcnt(1)
	v_mfma_f32_16x16x32_bf16 v[68:71], v[56:59], v[140:143], v[68:71]
	s_waitcnt lgkmcnt(0)
	v_mfma_f32_16x16x32_bf16 v[68:71], v[60:63], v[144:147], v[68:71]
	v_lshl_add_u32 v200, s14, 4, v103
	v_ashrrev_i32_e32 v201, 31, v200
	v_lshlrev_b64 v[200:201], 12, v[200:201]
	v_lshl_add_u64 v[200:201], v[78:79], 0, v[200:201]
	s_nop 3
	v_cvt_pk_bf16_f32 v68, v68, v69
	v_cvt_pk_bf16_f32 v69, v70, v71
	global_store_dwordx2 v[200:201], v[68:69], off
	s_cmp_eq_u32 s3, s2
	s_cbranch_scc1 .LBB0_848
	v_mov_b32_e32 v68, v36
	v_mov_b32_e32 v69, v37
	v_mov_b32_e32 v70, v38
	v_mov_b32_e32 v71, v39
	v_mov_b32_e32 v36, v40
	v_mov_b32_e32 v37, v41
	v_mov_b32_e32 v38, v42
	v_mov_b32_e32 v39, v43
	v_mov_b32_e32 v40, v44
	v_mov_b32_e32 v41, v45
	v_mov_b32_e32 v42, v46
	v_mov_b32_e32 v43, v47
	s_waitcnt vmcnt(1)
	v_mov_b32_e32 v44, v64
	v_mov_b32_e32 v45, v65
	v_mov_b32_e32 v46, v66
	v_mov_b32_e32 v47, v67
	s_branch .LBB0_841

.LBB0_912:
	s_or_b64 exec, exec, s[12:13]
	v_readfirstlane_b32 s12, v97
	s_mov_b32 m0, s12
	v_mfma_f32_16x16x32_bf16 v[132:135], v[4:7], v[68:71], 0
	v_mfma_f32_16x16x32_bf16 v[136:139], v[8:11], v[68:71], 0
	v_mfma_f32_16x16x32_bf16 v[140:143], v[12:15], v[68:71], 0
	v_mfma_f32_16x16x32_bf16 v[144:147], v[16:19], v[68:71], 0
	v_mfma_f32_16x16x32_bf16 v[148:151], v[20:23], v[68:71], 0
	v_mfma_f32_16x16x32_bf16 v[152:155], v[24:27], v[68:71], 0
	v_mfma_f32_16x16x32_bf16 v[156:159], v[28:31], v[68:71], 0
	v_mfma_f32_16x16x32_bf16 v[160:163], v[32:35], v[68:71], 0
	v_add_u32_e32 v196, v89, v93
	ds_write_b128 v196, v[132:135]
	ds_write_b128 v196, v[136:139] offset:64
	ds_write_b128 v196, v[140:143] offset:128
	ds_write_b128 v196, v[144:147] offset:192
	ds_write_b128 v196, v[148:151] offset:256
	ds_write_b128 v196, v[152:155] offset:320
	ds_write_b128 v196, v[156:159] offset:384
	ds_write_b128 v196, v[160:163] offset:448
	s_waitcnt lgkmcnt(0)
	s_and_b64 s[12:13], s[54:55], exec
	s_cbranch_scc0 .Ls5l_bwd
	ds_read_b64 v[164:165], v95
	ds_read_b64 v[166:167], v95 offset:528
	ds_read_b64 v[168:169], v95 offset:1056
	ds_read_b64 v[170:171], v95 offset:1584
	ds_read_b64 v[172:173], v95 offset:2112
	ds_read_b64 v[174:175], v95 offset:2640
	ds_read_b64 v[176:177], v95 offset:3168
	ds_read_b64 v[178:179], v95 offset:3696
	s_waitcnt lgkmcnt(7)
	v_fma_f32 v164, -v72, v121, v164
	v_fma_f32 v165, v72, v120, v165
	v_fma_f32 v164, v74, v120, v164
	v_fma_f32 v165, v74, v121, v165
	v_cvt_pk_bf16_f32 v197, v164, v165
	ds_write_addtid_b32 v197
	ds_read_b64 v[180:181], v95 offset:4224
	s_waitcnt lgkmcnt(8)
	v_fma_f32 v166, -v72, v165, v166
	v_fma_f32 v167, v72, v164, v167
	v_fma_f32 v166, v74, v164, v166
	v_fma_f32 v167, v74, v165, v167
	v_cvt_pk_bf16_f32 v198, v166, v167
	ds_write_addtid_b32 v198 offset:272
	ds_read_b64 v[182:183], v95 offset:4752
	s_waitcnt lgkmcnt(9)
	v_fma_f32 v168, -v72, v167, v168
	v_fma_f32 v169, v72, v166, v169
	v_fma_f32 v168, v74, v166, v168
	v_fma_f32 v169, v74, v167, v169
	v_cvt_pk_bf16_f32 v197, v168, v169
	ds_write_addtid_b32 v197 offset:544
	ds_read_b64 v[184:185], v95 offset:5280
	s_waitcnt lgkmcnt(10)
	v_fma_f32 v170, -v72, v169, v170
	v_fma_f32 v171, v72, v168, v171
	v_fma_f32 v170, v74, v168, v170
	v_fma_f32 v171, v74, v169, v171
	v_cvt_pk_bf16_f32 v198, v170, v171
	ds_write_addtid_b32 v198 offset:816
	ds_read_b64 v[186:187], v95 offset:5808
	s_waitcnt lgkmcnt(11)
	v_fma_f32 v172, -v72, v171, v172
	v_fma_f32 v173, v72, v170, v173
	v_fma_f32 v172, v74, v170, v172
	v_fma_f32 v173, v74, v171, v173
	v_cvt_pk_bf16_f32 v197, v172, v173
	ds_write_addtid_b32 v197 offset:1088
	ds_read_b64 v[188:189], v95 offset:6336
	s_waitcnt lgkmcnt(12)
	v_fma_f32 v174, -v72, v173, v174
	v_fma_f32 v175, v72, v172, v175
	v_fma_f32 v174, v74, v172, v174
	v_fma_f32 v175, v74, v173, v175
	v_cvt_pk_bf16_f32 v198, v174, v175
	ds_write_addtid_b32 v198 offset:1360
	ds_read_b64 v[190:191], v95 offset:6864
	s_waitcnt lgkmcnt(13)
	v_fma_f32 v176, -v72, v175, v176
	v_fma_f32 v177, v72, v174, v177
	v_fma_f32 v176, v74, v174, v176
	v_fma_f32 v177, v74, v175, v177
	v_cvt_pk_bf16_f32 v197, v176, v177
	ds_write_addtid_b32 v197 offset:1632
	ds_read_b64 v[192:193], v95 offset:7392
	s_waitcnt lgkmcnt(14)
	v_fma_f32 v178, -v72, v177, v178
	v_fma_f32 v179, v72, v176, v179
	v_fma_f32 v178, v74, v176, v178
	v_fma_f32 v179, v74, v177, v179
	v_cvt_pk_bf16_f32 v198, v178, v179
	ds_write_addtid_b32 v198 offset:1904
	ds_read_b64 v[194:195], v95 offset:7920
	s_waitcnt lgkmcnt(14)
	v_fma_f32 v180, -v72, v179, v180
	v_fma_f32 v181, v72, v178, v181
	v_fma_f32 v180, v74, v178, v180
	v_fma_f32 v181, v74, v179, v181
	v_cvt_pk_bf16_f32 v197, v180, v181
	ds_write_addtid_b32 v197 offset:2176
	s_waitcnt lgkmcnt(13)
	v_fma_f32 v182, -v72, v181, v182
	v_fma_f32 v183, v72, v180, v183
	v_fma_f32 v182, v74, v180, v182
	v_fma_f32 v183, v74, v181, v183
	v_cvt_pk_bf16_f32 v198, v182, v183
	ds_write_addtid_b32 v198 offset:2448
	s_waitcnt lgkmcnt(12)
	v_fma_f32 v184, -v72, v183, v184
	v_fma_f32 v185, v72, v182, v185
	v_fma_f32 v184, v74, v182, v184
	v_fma_f32 v185, v74, v183, v185
	v_cvt_pk_bf16_f32 v197, v184, v185
	ds_write_addtid_b32 v197 offset:2720
	s_waitcnt lgkmcnt(11)
	v_fma_f32 v186, -v72, v185, v186
	v_fma_f32 v187, v72, v184, v187
	v_fma_f32 v186, v74, v184, v186
	v_fma_f32 v187, v74, v185, v187
	v_cvt_pk_bf16_f32 v198, v186, v187
	ds_write_addtid_b32 v198 offset:2992
	s_waitcnt lgkmcnt(10)
	v_fma_f32 v188, -v72, v187, v188
	v_fma_f32 v189, v72, v186, v189
	v_fma_f32 v188, v74, v186, v188
	v_fma_f32 v189, v74, v187, v189
	v_cvt_pk_bf16_f32 v197, v188, v189
	ds_write_addtid_b32 v197 offset:3264
	s_waitcnt lgkmcnt(9)
	v_fma_f32 v190, -v72, v189, v190
	v_fma_f32 v191, v72, v188, v191
	v_fma_f32 v190, v74, v188, v190
	v_fma_f32 v191, v74, v189, v191
	v_cvt_pk_bf16_f32 v198, v190, v191
	ds_write_addtid_b32 v198 offset:3536
	s_waitcnt lgkmcnt(8)
	v_fma_f32 v192, -v72, v191, v192
	v_fma_f32 v193, v72, v190, v193
	v_fma_f32 v192, v74, v190, v192
	v_fma_f32 v193, v74, v191, v193
	v_cvt_pk_bf16_f32 v197, v192, v193
	ds_write_addtid_b32 v197 offset:3808
	s_waitcnt lgkmcnt(7)
	v_fma_f32 v194, -v72, v193, v194
	v_fma_f32 v195, v72, v192, v195
	v_fma_f32 v194, v74, v192, v194
	v_fma_f32 v195, v74, v193, v195
	v_cvt_pk_bf16_f32 v198, v194, v195
	ds_write_addtid_b32 v198 offset:4080
	s_branch .Ls5l_join

.Ls5l_join:
	v_mov_b32_e32 v120, v194
	v_mov_b32_e32 v121, v195
	s_waitcnt lgkmcnt(0)
	v_add_u32_e32 v196, v99, v93
	ds_read_b128 v[132:135], v196
	ds_read_b128 v[136:139], v196 offset:64
	ds_read_b128 v[140:143], v196 offset:128
	ds_read_b128 v[144:147], v196 offset:192
	s_not_b32 s12, s4
	s_add_i32 s15, s3, s12
	s_and_b64 s[12:13], s[54:55], exec
	s_cselect_b32 s12, s4, s15
	s_add_i32 s4, s4, 1
	s_waitcnt lgkmcnt(3)
	v_mfma_f32_16x16x32_bf16 v[68:71], v[48:51], v[132:135], 0
	s_waitcnt lgkmcnt(2)
	v_mfma_f32_16x16x32_bf16 v[68:71], v[52:55], v[136:139], v[68:71]
	s_waitcnt lgkmcnt(1)
	v_mfma_f32_16x16x32_bf16 v[68:71], v[56:59], v[140:143], v[68:71]
	s_waitcnt lgkmcnt(0)
	v_mfma_f32_16x16x32_bf16 v[68:71], v[60:63], v[144:147], v[68:71]
	v_lshl_add_u32 v200, s12, 4, v2
	v_ashrrev_i32_e32 v201, 31, v200
	v_lshlrev_b64 v[200:201], 12, v[200:201]
	v_lshl_add_u64 v[200:201], v[78:79], 0, v[200:201]
	s_nop 3
	v_cvt_pk_bf16_f32 v68, v68, v69
	v_cvt_pk_bf16_f32 v69, v70, v71
	global_store_dwordx2 v[200:201], v[68:69], off
	s_cmp_eq_u32 s4, s3
	s_cbranch_scc1 .LBB0_916
	v_mov_b32_e32 v68, v36
	v_mov_b32_e32 v69, v37
	v_mov_b32_e32 v70, v38
	v_mov_b32_e32 v71, v39
	v_mov_b32_e32 v36, v40
	v_mov_b32_e32 v37, v41
	v_mov_b32_e32 v38, v42
	v_mov_b32_e32 v39, v43
	v_mov_b32_e32 v40, v44
	v_mov_b32_e32 v41, v45
	v_mov_b32_e32 v42, v46
	v_mov_b32_e32 v43, v47
	s_waitcnt vmcnt(1)
	v_mov_b32_e32 v44, v64
	v_mov_b32_e32 v45, v65
	v_mov_b32_e32 v46, v66
	v_mov_b32_e32 v47, v67
	s_branch .LBB0_909
